# tail-weight transposes (w_out, w_pg*ln_ple, w_pp) also moved from prep into the scan's idle wave 7 (one item per lane in each of the first 18 steps)
# speedup vs baseline: 1.0154x; 1.0154x over previous
_Z10fwd_kernel6Params:
	s_mov_b32 s86, s2
	s_load_dwordx8 s[76:83], s[0:1], 0x60
	s_load_dwordx8 s[8:15], s[0:1], 0x40
	s_load_dword s2, s[0:1], 0x80
	v_cmp_eq_u32_e64 s[94:95], 0, v0
	s_waitcnt lgkmcnt(0)
	v_writelane_b32 v255, s2, 0
	v_writelane_b32 v255, s8, 41
	v_writelane_b32 v255, s9, 42
	v_writelane_b32 v255, s10, 43
	v_writelane_b32 v255, s11, 44
	v_writelane_b32 v255, s12, 45
	v_writelane_b32 v255, s13, 46
	v_writelane_b32 v255, s14, 47
	v_writelane_b32 v255, s15, 48
	s_and_saveexec_b64 s[4:5], s[94:95]
	s_cbranch_execz .LBB0_2
	s_add_i32 s2, 0, 0x20800
	v_mov_b32_e32 v1, 0
	v_mov_b32_e32 v2, s2
	s_add_i32 s2, 0, 0x20804
	ds_write_b32 v2, v1
	v_mov_b32_e32 v2, s2
	ds_write_b32 v2, v1

.LBB0_30:
	s_or_b64 exec, exec, s[6:7]
	s_add_u32 s88, s80, 0x36900000
	s_addc_u32 s89, s81, 0
	s_add_u32 s84, s80, 0x36d00000
	s_addc_u32 s85, s81, 0
	s_add_u32 s12, s80, 0x36ec0000
	s_movk_i32 s1, 0x400
	s_addc_u32 s13, s81, 0
	v_cmp_gt_i32_e32 vcc, s1, v10
	s_and_saveexec_b64 s[4:5], vcc
	s_cbranch_execz .LBB0_57
	v_ashrrev_i32_e32 v11, 31, v10
	s_ashr_i32 s1, s0, 31
	v_lshlrev_b64 v[2:3], 2, v[10:11]
	s_lshl_b64 s[6:7], s[0:1], 2
	s_mov_b64 s[8:9], 0
	s_movk_i32 s1, 0x3ff

.LBB0_384:
	s_or_b64 exec, exec, s[68:69]
	s_lshr_b32 s75, s74, 6
	s_cmpk_gt_u32 s74, 0xff
	s_mov_b64 s[0:1], -1
	s_cbranch_scc0 .LBB0_396
	s_setprio 1
	s_and_b32 s0, s94, 15
	s_lshl_b32 s72, s0, 22
	s_add_i32 s73, s75, -4
	s_cmp_lg_u32 s73, 0
	s_cselect_b64 s[0:1], -1, 0
	s_cmpk_lt_u32 s74, 0x1c0
	s_cselect_b64 s[68:69], -1, 0
	s_not_b32 s70, s75
	s_lshl_b32 s70, s70, 5
	s_and_b32 s87, s70, 32
	s_add_i32 s70, s75, -5
	v_or_b32_e32 v2, s87, v83
	s_cmp_lt_u32 s70, 2
	v_mul_u32_u24_e32 v3, 0x110, v2
	s_cselect_b64 s[70:71], -1, 0
	v_mul_u32_u24_e32 v105, 0x50, v2
	v_lshl_add_u32 v106, s73, 7, v90
	v_lshl_or_b32 v2, s73, 5, v83
	v_lshl_add_u32 v108, s73, 6, v91
	s_add_i32 s73, s87, s95
	s_waitcnt lgkmcnt(0)
	s_barrier
	s_add_i32 s73, s73, s86
	s_waitcnt lgkmcnt(0)
	s_barrier
	s_movk_i32 s88, 0x50
	s_lshl_b32 s73, s73, 1
	v_mul_lo_u32 v107, v2, s88
	s_or_b32 s72, s72, s73
	s_mov_b32 s73, s96
	v_mov_b32_e32 v2, 0
	s_mov_b32 s87, 1
	v_lshl_add_u64 v[80:81], v[78:79], 0, s[72:73]
	v_add_u32_e32 v109, v86, v3
	v_mov_b32_e32 v3, v2
	v_mov_b32_e32 v4, v2
	v_mov_b32_e32 v5, v2
	s_waitcnt vmcnt(0)
	v_mov_b32_e32 v6, v2
	v_mov_b32_e32 v7, v2
	v_mov_b32_e32 v8, v2
	v_mov_b32_e32 v9, v2
	v_mov_b32_e32 v10, v2
	v_mov_b32_e32 v11, v2
	v_mov_b32_e32 v12, v2
	v_mov_b32_e32 v13, v2
	v_mov_b32_e32 v14, v2
	v_mov_b32_e32 v15, v2
	v_mov_b32_e32 v16, v2
	v_mov_b32_e32 v17, v2
	v_mov_b32_e32 v18, v2
	v_mov_b32_e32 v19, v2
	v_mov_b32_e32 v20, v2
	v_mov_b32_e32 v21, v2
	v_mov_b32_e32 v22, v2
	v_mov_b32_e32 v23, v2
	v_mov_b32_e32 v24, v2
	v_mov_b32_e32 v25, v2
	v_mov_b32_e32 v26, v2
	v_mov_b32_e32 v27, v2
	v_mov_b32_e32 v28, v2
	v_mov_b32_e32 v29, v2
	v_mov_b32_e32 v30, v2
	v_mov_b32_e32 v31, v2
	v_mov_b32_e32 v32, v2
	v_mov_b32_e32 v33, v2
	s_and_b64 vcc, exec, s[68:69]
	s_cbranch_vccnz .Lmy_pc0_nosetup
	v_readlane_b32 s98, v255, 3
	v_readlane_b32 s99, v255, 4
	v_readlane_b32 s100, v255, 17
	s_nop 3
	s_lshl_b32 s101, s100, 18
	s_add_u32 s98, s98, s101
	s_addc_u32 s99, s99, 0
	v_lshlrev_b32_e32 v232, 4, v158
	v_mov_b32_e32 v233, 0
	v_lshl_add_u64 v[232:233], s[98:99], 0, v[232:233]
	s_lshl_b32 s101, s100, 17
	s_add_u32 s98, s80, s101
	s_addc_u32 s99, s81, 0
	s_add_u32 s98, s98, 0x34000000
	s_addc_u32 s99, s99, 0
	v_lshlrev_b32_e32 v234, 3, v158
	v_mov_b32_e32 v235, 0
	v_lshl_add_u64 v[234:235], s[98:99], 0, v[234:235]
	v_mov_b32_e32 v236, 0x800
	v_mov_b32_e32 v237, 0
	v_mov_b32_e32 v238, 0x400
	v_mov_b32_e32 v239, 0
	v_mov_b32_e32 v244, 0x100
	v_mov_b32_e32 v245, 0
	v_mov_b32_e32 v202, 0x1000
	v_mov_b32_e32 v203, 0
	v_mov_b32_e32 v195, 0
	global_load_dwordx4 v[224:227], v[232:233], off
	global_load_dwordx4 v[228:231], v[232:233], off offset:1024
	v_lshl_add_u64 v[232:233], v[232:233], 0, v[236:237]

.Lmy_pc0:
	s_waitcnt vmcnt(0)
	v_cvt_pk_bf16_f32 v240, v224, v225
	v_cvt_pk_bf16_f32 v241, v226, v227
	v_cvt_pk_bf16_f32 v242, v228, v229
	v_cvt_pk_bf16_f32 v243, v230, v231
	global_store_dwordx2 v[234:235], v[240:241], off
	global_store_dwordx2 v[234:235], v[242:243], off offset:512
	v_lshl_add_u64 v[234:235], v[234:235], 0, v[238:239]
	s_add_i32 s32, s87, -1
	s_cmp_gt_u32 s32, 18
	s_cbranch_scc1 .Lmy_tw0_done
	s_cmp_eq_u32 s32, 0
	s_cbranch_scc0 .Lmy_tw0_fin
	v_readlane_b32 s100, v255, 17
	v_readlane_b32 s98, v255, 41
	v_readlane_b32 s99, v255, 42
	s_nop 3
	s_lshr_b32 s101, s100, 1
	s_lshl_b32 s101, s101, 15
	s_add_u32 s98, s98, s101
	s_addc_u32 s99, s99, 0
	s_and_b32 s101, s100, 1
	s_lshl_b32 s101, s101, 11
	s_add_u32 s98, s98, s101
	s_addc_u32 s99, s99, 0
	v_lshlrev_b32_e32 v200, 2, v158
	v_mov_b32_e32 v201, 0
	v_lshl_add_u64 v[160:161], s[98:99], 0, v[200:201]
	v_lshl_add_u64 v[162:163], v[160:161], 0, v[202:203]
	v_lshl_add_u64 v[164:165], v[162:163], 0, v[202:203]
	v_lshl_add_u64 v[166:167], v[164:165], 0, v[202:203]
	v_lshl_add_u64 v[168:169], v[166:167], 0, v[202:203]
	v_lshl_add_u64 v[170:171], v[168:169], 0, v[202:203]
	v_lshl_add_u64 v[172:173], v[170:171], 0, v[202:203]
	v_lshl_add_u64 v[174:175], v[172:173], 0, v[202:203]
	s_add_u32 s98, s80, 0x36900000
	s_addc_u32 s99, s81, 0
	s_and_b32 s101, s100, 1
	s_lshl_b32 s101, s101, 20
	s_add_u32 s98, s98, s101
	s_addc_u32 s99, s99, 0
	s_lshr_b32 s101, s100, 1
	s_lshl_b32 s101, s101, 4
	s_add_u32 s98, s98, s101
	s_addc_u32 s99, s99, 0
	v_lshlrev_b32_e32 v200, 11, v158
	v_mov_b32_e32 v194, 0x20000
	v_lshl_add_u64 v[192:193], s[98:99], 0, v[200:201]
	s_branch .Lmy_tw0_issue
.Lmy_tw0_fin:
	s_cmp_lt_u32 s32, 9
	s_cbranch_scc1 .Lmy_tw0_noscale
	s_cmp_gt_u32 s32, 16
	s_cbranch_scc1 .Lmy_tw0_noscale
	v_mul_f32_e32 v176, v176, v184
	v_mul_f32_e32 v177, v177, v185
	v_mul_f32_e32 v178, v178, v186
	v_mul_f32_e32 v179, v179, v187
	v_mul_f32_e32 v180, v180, v188
	v_mul_f32_e32 v181, v181, v189
	v_mul_f32_e32 v182, v182, v190
	v_mul_f32_e32 v183, v183, v191
.Lmy_tw0_noscale:
	v_cvt_pk_bf16_f32 v196, v176, v177
	v_cvt_pk_bf16_f32 v197, v178, v179
	v_cvt_pk_bf16_f32 v198, v180, v181
	v_cvt_pk_bf16_f32 v199, v182, v183
	global_store_dwordx4 v[192:193], v[196:199], off
	v_lshl_add_u64 v[192:193], v[192:193], 0, v[194:195]
	s_cmp_eq_u32 s32, 8
	s_cbranch_scc0 .Lmy_tw0_n8
	v_readlane_b32 s100, v255, 17
	v_readlane_b32 s98, v255, 45
	v_readlane_b32 s99, v255, 46
	s_nop 3
	s_lshr_b32 s101, s100, 1
	s_lshl_b32 s101, s101, 15
	s_add_u32 s98, s98, s101
	s_addc_u32 s99, s99, 0
	s_and_b32 s101, s100, 1
	s_lshl_b32 s101, s101, 11
	s_add_u32 s98, s98, s101
	s_addc_u32 s99, s99, 0
	v_lshlrev_b32_e32 v200, 2, v158
	v_mov_b32_e32 v201, 0
	v_lshl_add_u64 v[160:161], s[98:99], 0, v[200:201]
	v_lshl_add_u64 v[162:163], v[160:161], 0, v[202:203]
	v_lshl_add_u64 v[164:165], v[162:163], 0, v[202:203]
	v_lshl_add_u64 v[166:167], v[164:165], 0, v[202:203]
	v_lshl_add_u64 v[168:169], v[166:167], 0, v[202:203]
	v_lshl_add_u64 v[170:171], v[168:169], 0, v[202:203]
	v_lshl_add_u64 v[172:173], v[170:171], 0, v[202:203]
	v_lshl_add_u64 v[174:175], v[172:173], 0, v[202:203]
	s_add_u32 s98, s80, 0x36b00000
	s_addc_u32 s99, s81, 0
	s_and_b32 s101, s100, 1
	s_lshl_b32 s101, s101, 20
	s_add_u32 s98, s98, s101
	s_addc_u32 s99, s99, 0
	s_lshr_b32 s101, s100, 1
	s_lshl_b32 s101, s101, 4
	s_add_u32 s98, s98, s101
	s_addc_u32 s99, s99, 0
	v_lshlrev_b32_e32 v200, 11, v158
	v_mov_b32_e32 v194, 0x20000
	v_lshl_add_u64 v[192:193], s[98:99], 0, v[200:201]
	v_readlane_b32 s98, v255, 43
	v_readlane_b32 s99, v255, 44
	s_nop 3
	s_lshr_b32 s101, s100, 1
	s_lshl_b32 s101, s101, 5
	s_add_u32 s98, s98, s101
	s_addc_u32 s99, s99, 0
	v_mov_b32_e32 v200, s98
	v_mov_b32_e32 v201, s99
	global_load_dwordx4 v[184:187], v[200:201], off
	global_load_dwordx4 v[188:191], v[200:201], off offset:16
	s_branch .Lmy_tw0_issue
.Lmy_tw0_n8:
	s_cmp_eq_u32 s32, 16
	s_cbranch_scc0 .Lmy_tw0_n16
	v_readlane_b32 s100, v255, 17
	v_readlane_b32 s98, v255, 47
	v_readlane_b32 s99, v255, 48
	s_nop 3
	s_lshr_b32 s101, s100, 3
	s_lshl_b32 s101, s101, 15
	s_add_u32 s98, s98, s101
	s_addc_u32 s99, s99, 0
	s_and_b32 s101, s100, 7
	s_lshl_b32 s101, s101, 9
	s_add_u32 s98, s98, s101
	s_addc_u32 s99, s99, 0
	v_lshlrev_b32_e32 v200, 2, v158
	v_mov_b32_e32 v201, 0
	v_lshl_add_u64 v[160:161], s[98:99], 0, v[200:201]
	v_lshl_add_u64 v[162:163], v[160:161], 0, v[202:203]
	v_lshl_add_u64 v[164:165], v[162:163], 0, v[202:203]
	v_lshl_add_u64 v[166:167], v[164:165], 0, v[202:203]
	v_lshl_add_u64 v[168:169], v[166:167], 0, v[202:203]
	v_lshl_add_u64 v[170:171], v[168:169], 0, v[202:203]
	v_lshl_add_u64 v[172:173], v[170:171], 0, v[202:203]
	v_lshl_add_u64 v[174:175], v[172:173], 0, v[202:203]
	s_add_u32 s98, s80, 0x36d00000
	s_addc_u32 s99, s81, 0
	s_and_b32 s101, s100, 7
	s_lshl_b32 s101, s101, 16
	s_add_u32 s98, s98, s101
	s_addc_u32 s99, s99, 0
	s_lshr_b32 s101, s100, 3
	s_lshl_b32 s101, s101, 4
	s_add_u32 s98, s98, s101
	s_addc_u32 s99, s99, 0
	v_lshlrev_b32_e32 v200, 9, v158
	v_mov_b32_e32 v194, 0x8000
	v_lshl_add_u64 v[192:193], s[98:99], 0, v[200:201]
	s_branch .Lmy_tw0_issue
.Lmy_tw0_n16:
	s_cmp_gt_u32 s32, 17
	s_cbranch_scc1 .Lmy_tw0_done
.Lmy_tw0_issue:
	global_load_dword v176, v[160:161], off
	v_lshl_add_u64 v[160:161], v[160:161], 0, v[244:245]
	global_load_dword v177, v[162:163], off
	v_lshl_add_u64 v[162:163], v[162:163], 0, v[244:245]
	global_load_dword v178, v[164:165], off
	v_lshl_add_u64 v[164:165], v[164:165], 0, v[244:245]
	global_load_dword v179, v[166:167], off
	v_lshl_add_u64 v[166:167], v[166:167], 0, v[244:245]
	global_load_dword v180, v[168:169], off
	v_lshl_add_u64 v[168:169], v[168:169], 0, v[244:245]
	global_load_dword v181, v[170:171], off
	v_lshl_add_u64 v[170:171], v[170:171], 0, v[244:245]
	global_load_dword v182, v[172:173], off
	v_lshl_add_u64 v[172:173], v[172:173], 0, v[244:245]
	global_load_dword v183, v[174:175], off
	v_lshl_add_u64 v[174:175], v[174:175], 0, v[244:245]
.Lmy_tw0_done:
	s_cmpk_eq_i32 s87, 0x80
	s_cbranch_scc1 .LBB0_392
	global_load_dwordx4 v[224:227], v[232:233], off
	global_load_dwordx4 v[228:231], v[232:233], off offset:1024
	v_lshl_add_u64 v[232:233], v[232:233], 0, v[236:237]
	s_branch .LBB0_392

.LBB0_415:
	s_or_b64 exec, exec, s[68:69]
	v_readfirstlane_b32 s88, v0
	s_lshl_b32 s0, s94, 12
	s_lshr_b32 s87, s88, 6
	s_cmpk_gt_u32 s88, 0xff
	s_mov_b64 s[68:69], -1
	s_cbranch_scc0 .LBB0_427
	s_setprio 1
	s_mov_b32 s1, s96
	s_lshl_b64 s[74:75], s[0:1], 10
	s_add_i32 s92, s87, -4
	s_cmp_lg_u32 s92, 0
	s_cselect_b64 s[68:69], -1, 0
	s_cmpk_lt_u32 s88, 0x1c0
	s_cselect_b64 s[70:71], -1, 0
	s_not_b32 s72, s87
	s_lshl_b32 s72, s72, 5
	s_and_b32 s93, s72, 32
	s_add_i32 s72, s87, -5
	v_or_b32_e32 v2, s93, v83
	s_cmp_lt_u32 s72, 2
	v_mul_u32_u24_e32 v3, 0x110, v2
	s_cselect_b64 s[72:73], -1, 0
	v_mul_u32_u24_e32 v105, 0x50, v2
	v_lshl_add_u32 v106, s92, 7, v90
	v_lshl_or_b32 v2, s92, 5, v83
	v_lshl_add_u32 v108, s92, 6, v91
	s_add_i32 s92, s93, s95
	s_add_i32 s92, s92, s86
	s_waitcnt lgkmcnt(0)
	s_barrier
	s_lshl_b32 s86, s92, 1
	s_waitcnt lgkmcnt(0)
	s_barrier
	s_movk_i32 vcc_lo, 0x50
	s_add_u32 s74, s74, s86
	v_mul_lo_u32 v107, v2, vcc_lo
	s_addc_u32 s75, s75, 0
	v_mov_b32_e32 v2, 0
	s_mov_b32 s1, 0
	v_lshl_add_u64 v[80:81], v[76:77], 0, s[74:75]
	s_mov_b64 s[74:75], 0
	v_add_u32_e32 v109, v86, v3
	v_mov_b32_e32 v3, v2
	v_mov_b32_e32 v4, v2
	v_mov_b32_e32 v5, v2
	s_waitcnt vmcnt(0)
	v_mov_b32_e32 v6, v2
	v_mov_b32_e32 v7, v2
	v_mov_b32_e32 v8, v2
	v_mov_b32_e32 v9, v2
	v_mov_b32_e32 v10, v2
	v_mov_b32_e32 v11, v2
	v_mov_b32_e32 v12, v2
	v_mov_b32_e32 v13, v2
	v_mov_b32_e32 v14, v2
	v_mov_b32_e32 v15, v2
	v_mov_b32_e32 v16, v2
	v_mov_b32_e32 v17, v2
	v_mov_b32_e32 v18, v2
	v_mov_b32_e32 v19, v2
	v_mov_b32_e32 v20, v2
	v_mov_b32_e32 v21, v2
	v_mov_b32_e32 v22, v2
	v_mov_b32_e32 v23, v2
	v_mov_b32_e32 v24, v2
	v_mov_b32_e32 v25, v2
	v_mov_b32_e32 v26, v2
	v_mov_b32_e32 v27, v2
	v_mov_b32_e32 v28, v2
	v_mov_b32_e32 v29, v2
	v_mov_b32_e32 v30, v2
	v_mov_b32_e32 v31, v2
	v_mov_b32_e32 v32, v2
	v_mov_b32_e32 v33, v2
	s_and_b64 vcc, exec, s[70:71]
	s_cbranch_vccnz .Lmy_pc1_nosetup
	v_readlane_b32 s98, v255, 3
	v_readlane_b32 s99, v255, 4
	v_readlane_b32 s100, v255, 17
	s_nop 3
	s_lshl_b32 s101, s100, 18
	s_add_u32 s98, s98, s101
	s_addc_u32 s99, s99, 0
	v_lshlrev_b32_e32 v232, 4, v158
	v_mov_b32_e32 v233, 0
	v_lshl_add_u64 v[232:233], s[98:99], 0, v[232:233]
	s_lshl_b32 s101, s100, 17
	s_add_u32 s98, s80, s101
	s_addc_u32 s99, s81, 0
	s_add_u32 s98, s98, 0x34000000
	s_addc_u32 s99, s99, 0
	v_lshlrev_b32_e32 v234, 3, v158
	v_mov_b32_e32 v235, 0
	v_lshl_add_u64 v[234:235], s[98:99], 0, v[234:235]
	v_mov_b32_e32 v236, 0x800
	v_mov_b32_e32 v237, 0
	v_mov_b32_e32 v238, 0x400
	v_mov_b32_e32 v239, 0
	v_mov_b32_e32 v244, 0x100
	v_mov_b32_e32 v245, 0
	v_mov_b32_e32 v202, 0x1000
	v_mov_b32_e32 v203, 0
	v_mov_b32_e32 v195, 0
	global_load_dwordx4 v[224:227], v[232:233], off
	global_load_dwordx4 v[228:231], v[232:233], off offset:1024
	v_lshl_add_u64 v[232:233], v[232:233], 0, v[236:237]

.Lmy_pc1:
	s_waitcnt vmcnt(0)
	v_cvt_pk_bf16_f32 v240, v224, v225
	v_cvt_pk_bf16_f32 v241, v226, v227
	v_cvt_pk_bf16_f32 v242, v228, v229
	v_cvt_pk_bf16_f32 v243, v230, v231
	global_store_dwordx2 v[234:235], v[240:241], off
	global_store_dwordx2 v[234:235], v[242:243], off offset:512
	v_lshl_add_u64 v[234:235], v[234:235], 0, v[238:239]
	s_mov_b32 s32, s1
	s_cmp_gt_u32 s32, 18
	s_cbranch_scc1 .Lmy_tw1_done
	s_cmp_eq_u32 s32, 0
	s_cbranch_scc0 .Lmy_tw1_fin
	v_readlane_b32 s100, v255, 17
	v_readlane_b32 s98, v255, 41
	v_readlane_b32 s99, v255, 42
	s_nop 3
	s_lshr_b32 s101, s100, 1
	s_lshl_b32 s101, s101, 15
	s_add_u32 s98, s98, s101
	s_addc_u32 s99, s99, 0
	s_and_b32 s101, s100, 1
	s_lshl_b32 s101, s101, 11
	s_add_u32 s98, s98, s101
	s_addc_u32 s99, s99, 0
	v_lshlrev_b32_e32 v200, 2, v158
	v_mov_b32_e32 v201, 0
	v_lshl_add_u64 v[160:161], s[98:99], 0, v[200:201]
	v_lshl_add_u64 v[162:163], v[160:161], 0, v[202:203]
	v_lshl_add_u64 v[164:165], v[162:163], 0, v[202:203]
	v_lshl_add_u64 v[166:167], v[164:165], 0, v[202:203]
	v_lshl_add_u64 v[168:169], v[166:167], 0, v[202:203]
	v_lshl_add_u64 v[170:171], v[168:169], 0, v[202:203]
	v_lshl_add_u64 v[172:173], v[170:171], 0, v[202:203]
	v_lshl_add_u64 v[174:175], v[172:173], 0, v[202:203]
	s_add_u32 s98, s80, 0x36900000
	s_addc_u32 s99, s81, 0
	s_and_b32 s101, s100, 1
	s_lshl_b32 s101, s101, 20
	s_add_u32 s98, s98, s101
	s_addc_u32 s99, s99, 0
	s_lshr_b32 s101, s100, 1
	s_lshl_b32 s101, s101, 4
	s_add_u32 s98, s98, s101
	s_addc_u32 s99, s99, 0
	v_lshlrev_b32_e32 v200, 11, v158
	v_mov_b32_e32 v194, 0x20000
	v_lshl_add_u64 v[192:193], s[98:99], 0, v[200:201]
	s_branch .Lmy_tw1_issue

.Lmy_tw1_done:
	s_cmpk_eq_i32 s1, 0x7f
	s_cbranch_scc1 .LBB0_421
	global_load_dwordx4 v[224:227], v[232:233], off
	global_load_dwordx4 v[228:231], v[232:233], off offset:1024
	v_lshl_add_u64 v[232:233], v[232:233], 0, v[236:237]
	s_branch .LBB0_421
